# layer-1 attention queue: next unit's ticket requested at the start of the current unit's epilogue (round trip hidden), loop top only reads it (on v74)
# speedup vs baseline: 1.0069x; 1.0069x over previous
.LBB0_294:
	s_barrier
	s_and_saveexec_b64 s[4:5], s[0:1]
	s_cbranch_execz .LBB0_298
	s_waitcnt vmcnt(0)
	v_readfirstlane_b32 s6, v250
	v_mov_b32_e32 v2, s33
	v_mov_b32_e32 v1, s6
	ds_write_b32 v2, v1

.LBB0_411:
	s_and_saveexec_b64 s[100:101], s[0:1]
	v_mov_b32_e32 v250, 1
	s_cbranch_execz .Lpf_l1_next
	global_atomic_add v250, v0, v250, s[34:35] sc0
.Lpf_l1_next:
	s_or_b64 exec, exec, s[100:101]
	ds_bpermute_b32 v1, v200, v245
	s_waitcnt lgkmcnt(0)
	v_add_f32_e32 v1, v245, v1
	v_div_scale_f32 v2, s[8:9], v1, v1, 1.0
	v_rcp_f32_e32 v3, v2
	v_readlane_b32 s8, v254, 1
	v_readlane_b32 s9, v254, 2
	v_fma_f32 v4, -v2, v3, 1.0
	v_fmac_f32_e32 v3, v4, v3
	v_div_scale_f32 v4, vcc, 1.0, v1, 1.0
	v_mul_f32_e32 v5, v4, v3
	v_fma_f32 v6, -v2, v5, v4
	v_fmac_f32_e32 v5, v6, v3
	v_fma_f32 v2, -v2, v5, v4
	v_div_fmas_f32 v2, v2, v3, v5
	v_div_fixup_f32 v80, v2, v1, 1.0
	s_andn2_b64 vcc, exec, s[8:9]
	s_cbranch_vccnz .LBB0_413
	v_readlane_b32 s5, v253, 61
	v_mul_f32_e32 v2, v80, v64
	v_mul_f32_e32 v3, v80, v65
	v_lshl_add_u32 v1, v187, 2, s5
	ds_write2st64_b32 v1, v2, v3 offset1:1
	v_mul_f32_e32 v2, v80, v66
	v_mul_f32_e32 v3, v80, v67
	ds_write2st64_b32 v1, v2, v3 offset0:2 offset1:3
	v_mul_f32_e32 v2, v80, v68
	v_mul_f32_e32 v3, v80, v69
	ds_write2st64_b32 v1, v2, v3 offset0:4 offset1:5
	v_mul_f32_e32 v2, v80, v70
	v_mul_f32_e32 v3, v80, v71
	ds_write2st64_b32 v1, v2, v3 offset0:6 offset1:7
	v_mul_f32_e32 v2, v80, v72
	v_mul_f32_e32 v3, v80, v73
	ds_write2st64_b32 v1, v2, v3 offset0:8 offset1:9
	v_mul_f32_e32 v2, v80, v74
	v_mul_f32_e32 v3, v80, v75
	ds_write2st64_b32 v1, v2, v3 offset0:10 offset1:11
	v_mul_f32_e32 v2, v80, v76
	v_mul_f32_e32 v3, v80, v77
	ds_write2st64_b32 v1, v2, v3 offset0:12 offset1:13
	v_mul_f32_e32 v2, v80, v78
	v_mul_f32_e32 v3, v80, v79
	ds_write2st64_b32 v1, v2, v3 offset0:14 offset1:15
	v_mul_f32_e32 v2, v80, v48
	v_mul_f32_e32 v3, v80, v49
	ds_write2st64_b32 v1, v2, v3 offset0:16 offset1:17
	v_mul_f32_e32 v2, v80, v50
	v_mul_f32_e32 v3, v80, v51
	ds_write2st64_b32 v1, v2, v3 offset0:18 offset1:19
	v_mul_f32_e32 v2, v80, v52
	v_mul_f32_e32 v3, v80, v53
	ds_write2st64_b32 v1, v2, v3 offset0:20 offset1:21
	v_mul_f32_e32 v2, v80, v54
	v_mul_f32_e32 v3, v80, v55
	ds_write2st64_b32 v1, v2, v3 offset0:22 offset1:23
	v_mul_f32_e32 v2, v80, v56
	v_mul_f32_e32 v3, v80, v57
	ds_write2st64_b32 v1, v2, v3 offset0:24 offset1:25
	v_mul_f32_e32 v2, v80, v58
	v_mul_f32_e32 v3, v80, v59
	ds_write2st64_b32 v1, v2, v3 offset0:26 offset1:27
	v_mul_f32_e32 v2, v80, v60
	v_mul_f32_e32 v3, v80, v61
	ds_write2st64_b32 v1, v2, v3 offset0:28 offset1:29
	v_mul_f32_e32 v2, v80, v62
	v_mul_f32_e32 v3, v80, v63
	ds_write2st64_b32 v1, v2, v3 offset0:30 offset1:31
	v_mul_f32_e32 v2, v80, v32
	v_mul_f32_e32 v3, v80, v33
	ds_write2st64_b32 v1, v2, v3 offset0:32 offset1:33
	v_mul_f32_e32 v2, v80, v34
	v_mul_f32_e32 v3, v80, v35
	ds_write2st64_b32 v1, v2, v3 offset0:34 offset1:35
	v_mul_f32_e32 v2, v80, v36
	v_mul_f32_e32 v3, v80, v37
	ds_write2st64_b32 v1, v2, v3 offset0:36 offset1:37
	v_mul_f32_e32 v2, v80, v38
	v_mul_f32_e32 v3, v80, v39
	ds_write2st64_b32 v1, v2, v3 offset0:38 offset1:39
	v_mul_f32_e32 v2, v80, v40
	v_mul_f32_e32 v3, v80, v41
	ds_write2st64_b32 v1, v2, v3 offset0:40 offset1:41
	v_mul_f32_e32 v2, v80, v42
	v_mul_f32_e32 v3, v80, v43
	ds_write2st64_b32 v1, v2, v3 offset0:42 offset1:43
	v_mul_f32_e32 v2, v80, v44
	v_mul_f32_e32 v3, v80, v45
	ds_write2st64_b32 v1, v2, v3 offset0:44 offset1:45
	v_mul_f32_e32 v2, v80, v46
	v_mul_f32_e32 v3, v80, v47
	ds_write2st64_b32 v1, v2, v3 offset0:46 offset1:47
	v_mul_f32_e32 v2, v80, v16
	v_mul_f32_e32 v3, v80, v17
	ds_write2st64_b32 v1, v2, v3 offset0:48 offset1:49
	v_mul_f32_e32 v2, v80, v18
	v_mul_f32_e32 v3, v80, v19
	ds_write2st64_b32 v1, v2, v3 offset0:50 offset1:51
	v_mul_f32_e32 v2, v80, v20
	v_mul_f32_e32 v3, v80, v21
	ds_write2st64_b32 v1, v2, v3 offset0:52 offset1:53
	v_mul_f32_e32 v2, v80, v22
	v_mul_f32_e32 v3, v80, v23
	ds_write2st64_b32 v1, v2, v3 offset0:54 offset1:55
	v_mul_f32_e32 v2, v80, v24
	v_mul_f32_e32 v3, v80, v25
	ds_write2st64_b32 v1, v2, v3 offset0:56 offset1:57
	v_mul_f32_e32 v2, v80, v26
	v_mul_f32_e32 v3, v80, v27
	ds_write2st64_b32 v1, v2, v3 offset0:58 offset1:59
	v_mul_f32_e32 v2, v80, v28
	v_mul_f32_e32 v3, v80, v29
	ds_write2st64_b32 v1, v2, v3 offset0:60 offset1:61
	v_mul_f32_e32 v2, v80, v30
	v_mul_f32_e32 v3, v80, v31
	ds_write2st64_b32 v1, v2, v3 offset0:62 offset1:63
